# select search: when the last key block only fills lanes 0-31, fold its 32 registers into 16 with permlane32 swaps for the count passes (undone before the emit)
# speedup vs baseline: 1.0108x; 1.0055x over previous
; __device__ __forceinline__ void select_query(const unsigned (&u)[64], unsigned vmax, int q, int b, int lane, unsigned* MASKb) {
;     const int n = q + 1, nblk = (n + 2047) >> 11;
;     unsigned T = 0u, TG = 0u; int rrem = 0;
;     if (n > 256) {
;         const unsigned kmax = wave_umax(vmax);
;         const unsigned K0 = 0x80000000u;
;         bool exact = false, done = false;
;         unsigned lo = 0u, hi = 0u; float Llo = 1.f, Lhi = 1.f;
;         const float L256 = 8.0028150156f;
;         const int cpos = count_ge(u, K0 + 1u, nblk);
.LBB0_130:
	v_add_u32_e32 v0, 0x800, v106
	v_ashrrev_i32_e32 v190, 11, v0
	s_mov_b64 s[8:9], exec
	v_mov_b32_e32 v192, 0
	v_mov_b32_e32 v193, 0
	v_mov_b32_e32 v191, 0
	s_cmpk_gt_i32 s75, 0xff
	s_cbranch_scc0 .Lsqa_done
	s_add_i32 s25, s75, 0x800
	s_lshr_b32 s25, s25, 11
	s_add_i32 s26, s75, 0
	s_lshl_b32 s32, s25, 1
	s_bitcmp0_b32 s26, 10
	s_subb_u32 s32, s32, 0
	s_bitcmp1_b32 s32, 0
	s_cbranch_scc0 .Lsqa_fon
	s_cmp_lt_u32 s32, 2
	s_cbranch_scc0 .Lsqa_fo1
	v_permlane32_swap_b32_e32 v138, v153
	v_permlane32_swap_b32_e32 v140, v156
	v_permlane32_swap_b32_e32 v139, v155
	v_permlane32_swap_b32_e32 v141, v157
	v_permlane32_swap_b32_e32 v142, v158
	v_permlane32_swap_b32_e32 v146, v160
	v_permlane32_swap_b32_e32 v143, v159
	v_permlane32_swap_b32_e32 v147, v161
	v_permlane32_swap_b32_e32 v144, v167
	v_permlane32_swap_b32_e32 v148, v169
	v_permlane32_swap_b32_e32 v145, v168
	v_permlane32_swap_b32_e32 v149, v170
	v_permlane32_swap_b32_e32 v150, v173
	v_permlane32_swap_b32_e32 v152, v174
	v_permlane32_swap_b32_e32 v151, v175
	v_permlane32_swap_b32_e32 v154, v176
	s_branch .Lsqa_fon
.Lsqa_fo1:
	v_permlane32_swap_b32_e32 v76, v92
	v_permlane32_swap_b32_e32 v78, v95
	v_permlane32_swap_b32_e32 v77, v94
	v_permlane32_swap_b32_e32 v79, v96
	v_permlane32_swap_b32_e32 v80, v97
	v_permlane32_swap_b32_e32 v84, v172
	v_permlane32_swap_b32_e32 v81, v171
	v_permlane32_swap_b32_e32 v85, v178
	v_permlane32_swap_b32_e32 v82, v180
	v_permlane32_swap_b32_e32 v86, v183
	v_permlane32_swap_b32_e32 v83, v182
	v_permlane32_swap_b32_e32 v87, v184
	v_permlane32_swap_b32_e32 v89, v186
	v_permlane32_swap_b32_e32 v91, v187
	v_permlane32_swap_b32_e32 v90, v188
	v_permlane32_swap_b32_e32 v93, v189
.Lsqa_fon:
	s_nop 1
	v_max_u32_dpp v191, v185, v185 row_shr:1 row_mask:0xf bank_mask:0xf bound_ctrl:1
	s_nop 1
	v_max_u32_dpp v191, v191, v191 row_shr:2 row_mask:0xf bank_mask:0xf bound_ctrl:1
	s_nop 1
	v_max_u32_dpp v191, v191, v191 row_shr:4 row_mask:0xf bank_mask:0xf bound_ctrl:1
	s_nop 1
	v_max_u32_dpp v191, v191, v191 row_shr:8 row_mask:0xf bank_mask:0xf bound_ctrl:1
	s_nop 1
	v_max_u32_dpp v191, v191, v191 row_bcast:15 row_mask:0xa bank_mask:0xf
	s_nop 1
	v_max_u32_dpp v191, v191, v191 row_bcast:31 row_mask:0xc bank_mask:0xf
	s_nop 0
	v_readlane_b32 s19, v191, 63
	s_mov_b32 s21, 0
	s_mov_b32 s14, 0x80000001
; __device__ __forceinline__ int count_ge(const unsigned (&u)[64], unsigned cand, int nblk) {
;     int c0 = 0, c1 = 0;
;     const unsigned ts = __builtin_amdgcn_readfirstlane(cand);
; #pragma unroll
;     for (int B = 0; B < 2; ++B) {
;         if (B < nblk) {
; #pragma unroll
;             for (int i = 0; i < 32; i += 4) CNT4(c0, c1, ts, u[B * 32 + i], u[B * 32 + i + 1], u[B * 32 + i + 2], u[B * 32 + i + 3]);
;         }
;     }
;     return wave_isum(c0 + c1);
; }
.Lsqa_count:
	v_mov_b32_e32 v0, 0
	v_mov_b32_e32 v34, 0
	v_cmp_le_u32_e64 s[4:5], s14, v138
	v_cmp_le_u32_e64 s[6:7], s14, v140
	v_cmp_le_u32_e64 s[10:11], s14, v139
	v_cmp_le_u32_e64 s[26:27], s14, v141
	v_addc_co_u32_e64 v0, s[28:29], 0, v0, s[4:5]
	v_addc_co_u32_e64 v34, s[30:31], 0, v34, s[6:7]
	v_addc_co_u32_e64 v0, s[28:29], 0, v0, s[10:11]
	v_addc_co_u32_e64 v34, s[30:31], 0, v34, s[26:27]
	v_cmp_le_u32_e64 s[4:5], s14, v142
	v_cmp_le_u32_e64 s[6:7], s14, v146
	v_cmp_le_u32_e64 s[10:11], s14, v143
	v_cmp_le_u32_e64 s[26:27], s14, v147
	v_addc_co_u32_e64 v0, s[28:29], 0, v0, s[4:5]
	v_addc_co_u32_e64 v34, s[30:31], 0, v34, s[6:7]
	v_addc_co_u32_e64 v0, s[28:29], 0, v0, s[10:11]
	v_addc_co_u32_e64 v34, s[30:31], 0, v34, s[26:27]
	v_cmp_le_u32_e64 s[4:5], s14, v144
	v_cmp_le_u32_e64 s[6:7], s14, v148
	v_cmp_le_u32_e64 s[10:11], s14, v145
	v_cmp_le_u32_e64 s[26:27], s14, v149
	v_addc_co_u32_e64 v0, s[28:29], 0, v0, s[4:5]
	v_addc_co_u32_e64 v34, s[30:31], 0, v34, s[6:7]
	v_addc_co_u32_e64 v0, s[28:29], 0, v0, s[10:11]
	v_addc_co_u32_e64 v34, s[30:31], 0, v34, s[26:27]
	v_cmp_le_u32_e64 s[4:5], s14, v150
	v_cmp_le_u32_e64 s[6:7], s14, v152
	v_cmp_le_u32_e64 s[10:11], s14, v151
	v_cmp_le_u32_e64 s[26:27], s14, v154
	v_addc_co_u32_e64 v0, s[28:29], 0, v0, s[4:5]
	v_addc_co_u32_e64 v34, s[30:31], 0, v34, s[6:7]
	v_addc_co_u32_e64 v0, s[28:29], 0, v0, s[10:11]
	v_addc_co_u32_e64 v34, s[30:31], 0, v34, s[26:27]
	s_cmp_eq_u32 s32, 1
	s_cbranch_scc1 .Lsqa_red
	v_cmp_le_u32_e64 s[4:5], s14, v153
	v_cmp_le_u32_e64 s[6:7], s14, v156
	v_cmp_le_u32_e64 s[10:11], s14, v155
	v_cmp_le_u32_e64 s[26:27], s14, v157
	v_addc_co_u32_e64 v0, s[28:29], 0, v0, s[4:5]
	v_addc_co_u32_e64 v34, s[30:31], 0, v34, s[6:7]
	v_addc_co_u32_e64 v0, s[28:29], 0, v0, s[10:11]
	v_addc_co_u32_e64 v34, s[30:31], 0, v34, s[26:27]
	v_cmp_le_u32_e64 s[4:5], s14, v158
	v_cmp_le_u32_e64 s[6:7], s14, v160
	v_cmp_le_u32_e64 s[10:11], s14, v159
	v_cmp_le_u32_e64 s[26:27], s14, v161
	v_addc_co_u32_e64 v0, s[28:29], 0, v0, s[4:5]
	v_addc_co_u32_e64 v34, s[30:31], 0, v34, s[6:7]
	v_addc_co_u32_e64 v0, s[28:29], 0, v0, s[10:11]
	v_addc_co_u32_e64 v34, s[30:31], 0, v34, s[26:27]
	v_cmp_le_u32_e64 s[4:5], s14, v167
	v_cmp_le_u32_e64 s[6:7], s14, v169
	v_cmp_le_u32_e64 s[10:11], s14, v168
	v_cmp_le_u32_e64 s[26:27], s14, v170
	v_addc_co_u32_e64 v0, s[28:29], 0, v0, s[4:5]
	v_addc_co_u32_e64 v34, s[30:31], 0, v34, s[6:7]
	v_addc_co_u32_e64 v0, s[28:29], 0, v0, s[10:11]
	v_addc_co_u32_e64 v34, s[30:31], 0, v34, s[26:27]
	v_cmp_le_u32_e64 s[4:5], s14, v173
	v_cmp_le_u32_e64 s[6:7], s14, v174
	v_cmp_le_u32_e64 s[10:11], s14, v175
	v_cmp_le_u32_e64 s[26:27], s14, v176
	v_addc_co_u32_e64 v0, s[28:29], 0, v0, s[4:5]
	v_addc_co_u32_e64 v34, s[30:31], 0, v34, s[6:7]
	v_addc_co_u32_e64 v0, s[28:29], 0, v0, s[10:11]
	v_addc_co_u32_e64 v34, s[30:31], 0, v34, s[26:27]
	s_cmp_eq_u32 s32, 2
	s_cbranch_scc1 .Lsqa_red
	v_cmp_le_u32_e64 s[4:5], s14, v76
	v_cmp_le_u32_e64 s[6:7], s14, v78
	v_cmp_le_u32_e64 s[10:11], s14, v77
	v_cmp_le_u32_e64 s[26:27], s14, v79
	v_addc_co_u32_e64 v0, s[28:29], 0, v0, s[4:5]
	v_addc_co_u32_e64 v34, s[30:31], 0, v34, s[6:7]
	v_addc_co_u32_e64 v0, s[28:29], 0, v0, s[10:11]
	v_addc_co_u32_e64 v34, s[30:31], 0, v34, s[26:27]
	v_cmp_le_u32_e64 s[4:5], s14, v80
	v_cmp_le_u32_e64 s[6:7], s14, v84
	v_cmp_le_u32_e64 s[10:11], s14, v81
	v_cmp_le_u32_e64 s[26:27], s14, v85
	v_addc_co_u32_e64 v0, s[28:29], 0, v0, s[4:5]
	v_addc_co_u32_e64 v34, s[30:31], 0, v34, s[6:7]
	v_addc_co_u32_e64 v0, s[28:29], 0, v0, s[10:11]
	v_addc_co_u32_e64 v34, s[30:31], 0, v34, s[26:27]
	v_cmp_le_u32_e64 s[4:5], s14, v82
	v_cmp_le_u32_e64 s[6:7], s14, v86
	v_cmp_le_u32_e64 s[10:11], s14, v83
	v_cmp_le_u32_e64 s[26:27], s14, v87
	v_addc_co_u32_e64 v0, s[28:29], 0, v0, s[4:5]
	v_addc_co_u32_e64 v34, s[30:31], 0, v34, s[6:7]
	v_addc_co_u32_e64 v0, s[28:29], 0, v0, s[10:11]
	v_addc_co_u32_e64 v34, s[30:31], 0, v34, s[26:27]
	v_cmp_le_u32_e64 s[4:5], s14, v89
	v_cmp_le_u32_e64 s[6:7], s14, v91
	v_cmp_le_u32_e64 s[10:11], s14, v90
	v_cmp_le_u32_e64 s[26:27], s14, v93
	v_addc_co_u32_e64 v0, s[28:29], 0, v0, s[4:5]
	v_addc_co_u32_e64 v34, s[30:31], 0, v34, s[6:7]
	v_addc_co_u32_e64 v0, s[28:29], 0, v0, s[10:11]
	v_addc_co_u32_e64 v34, s[30:31], 0, v34, s[26:27]
	s_cmp_eq_u32 s32, 3
	s_cbranch_scc1 .Lsqa_red
	v_cmp_le_u32_e64 s[4:5], s14, v92
	v_cmp_le_u32_e64 s[6:7], s14, v95
	v_cmp_le_u32_e64 s[10:11], s14, v94
	v_cmp_le_u32_e64 s[26:27], s14, v96
	v_addc_co_u32_e64 v0, s[28:29], 0, v0, s[4:5]
	v_addc_co_u32_e64 v34, s[30:31], 0, v34, s[6:7]
	v_addc_co_u32_e64 v0, s[28:29], 0, v0, s[10:11]
	v_addc_co_u32_e64 v34, s[30:31], 0, v34, s[26:27]
	v_cmp_le_u32_e64 s[4:5], s14, v97
	v_cmp_le_u32_e64 s[6:7], s14, v172
	v_cmp_le_u32_e64 s[10:11], s14, v171
	v_cmp_le_u32_e64 s[26:27], s14, v178
	v_addc_co_u32_e64 v0, s[28:29], 0, v0, s[4:5]
	v_addc_co_u32_e64 v34, s[30:31], 0, v34, s[6:7]
	v_addc_co_u32_e64 v0, s[28:29], 0, v0, s[10:11]
	v_addc_co_u32_e64 v34, s[30:31], 0, v34, s[26:27]
	v_cmp_le_u32_e64 s[4:5], s14, v180
	v_cmp_le_u32_e64 s[6:7], s14, v183
	v_cmp_le_u32_e64 s[10:11], s14, v182
	v_cmp_le_u32_e64 s[26:27], s14, v184
	v_addc_co_u32_e64 v0, s[28:29], 0, v0, s[4:5]
	v_addc_co_u32_e64 v34, s[30:31], 0, v34, s[6:7]
	v_addc_co_u32_e64 v0, s[28:29], 0, v0, s[10:11]
	v_addc_co_u32_e64 v34, s[30:31], 0, v34, s[26:27]
	v_cmp_le_u32_e64 s[4:5], s14, v186
	v_cmp_le_u32_e64 s[6:7], s14, v187
	v_cmp_le_u32_e64 s[10:11], s14, v188
	v_cmp_le_u32_e64 s[26:27], s14, v189
	v_addc_co_u32_e64 v0, s[28:29], 0, v0, s[4:5]
	v_addc_co_u32_e64 v34, s[30:31], 0, v34, s[6:7]
	v_addc_co_u32_e64 v0, s[28:29], 0, v0, s[10:11]
	v_addc_co_u32_e64 v34, s[30:31], 0, v34, s[26:27]

; __device__ __forceinline__ void select_query(const unsigned (&u)[64], unsigned vmax, int q, int b, int lane, unsigned* MASKb) {
;     ...
;         if (exact) TG = T - 1u; else { TG = T; rrem = 256 - count_ge(u, T + 1u, nblk); }
;     }
;     int tbase = 0;
; #pragma unroll
;     for (int B = 0; B < 2; ++B) {
;         if (B < nblk) {
;             unsigned w = 0u; const unsigned tgs = __builtin_amdgcn_readfirstlane(TG);
; #pragma unroll
;             for (int e = 31; e >= 3; e -= 4) BIT4(w, tgs, u[B * 32 + e], u[B * 32 + e - 1], u[B * 32 + e - 2], u[B * 32 + e - 3]);
.Lsqa_fin:
	s_bitcmp1_b32 s32, 0
	s_cbranch_scc0 .Lsqa_unn
	s_cmp_lt_u32 s32, 2
	s_cbranch_scc0 .Lsqa_un1
	v_permlane32_swap_b32_e32 v138, v153
	v_permlane32_swap_b32_e32 v140, v156
	v_permlane32_swap_b32_e32 v139, v155
	v_permlane32_swap_b32_e32 v141, v157
	v_permlane32_swap_b32_e32 v142, v158
	v_permlane32_swap_b32_e32 v146, v160
	v_permlane32_swap_b32_e32 v143, v159
	v_permlane32_swap_b32_e32 v147, v161
	v_permlane32_swap_b32_e32 v144, v167
	v_permlane32_swap_b32_e32 v148, v169
	v_permlane32_swap_b32_e32 v145, v168
	v_permlane32_swap_b32_e32 v149, v170
	v_permlane32_swap_b32_e32 v150, v173
	v_permlane32_swap_b32_e32 v152, v174
	v_permlane32_swap_b32_e32 v151, v175
	v_permlane32_swap_b32_e32 v154, v176
	s_branch .Lsqa_unn

; __device__ __forceinline__ void select_query(const unsigned (&u)[64], unsigned vmax, int q, int b, int lane, unsigned* MASKb) {
;     const int n = q + 1, nblk = (n + 2047) >> 11;
;     unsigned T = 0u, TG = 0u; int rrem = 0;
;     if (n > 256) {
;         const unsigned kmax = wave_umax(vmax);
;         const unsigned K0 = 0x80000000u;
;         bool exact = false, done = false;
;         unsigned lo = 0u, hi = 0u; float Llo = 1.f, Lhi = 1.f;
;         const float L256 = 8.0028150156f;
;         const int cpos = count_ge(u, K0 + 1u, nblk);
.LBB0_184:
	s_or_b64 exec, exec, s[70:71]
	v_add_u32_e32 v0, 0x801, v106
	v_ashrrev_i32_e32 v0, 11, v0
	s_mov_b64 s[8:9], exec
	v_mov_b32_e32 v76, 0
	v_mov_b32_e32 v77, 0
	v_mov_b32_e32 v69, 0
	s_cmpk_gt_i32 s75, 0xfe
	s_cbranch_scc0 .Lsqb_done
	s_add_i32 s25, s75, 0x801
	s_lshr_b32 s25, s25, 11
	s_add_i32 s26, s75, 1
	s_lshl_b32 s32, s25, 1
	s_bitcmp0_b32 s26, 10
	s_subb_u32 s32, s32, 0
	s_bitcmp1_b32 s32, 0
	s_cbranch_scc0 .Lsqb_fon
	s_cmp_lt_u32 s32, 2
	s_cbranch_scc0 .Lsqb_fo1
	v_permlane32_swap_b32_e32 v98, v120
	v_permlane32_swap_b32_e32 v107, v123
	v_permlane32_swap_b32_e32 v99, v122
	v_permlane32_swap_b32_e32 v108, v124
	v_permlane32_swap_b32_e32 v109, v125
	v_permlane32_swap_b32_e32 v113, v127
	v_permlane32_swap_b32_e32 v110, v126
	v_permlane32_swap_b32_e32 v114, v128
	v_permlane32_swap_b32_e32 v111, v129
	v_permlane32_swap_b32_e32 v115, v131
	v_permlane32_swap_b32_e32 v112, v130
	v_permlane32_swap_b32_e32 v116, v132
	v_permlane32_swap_b32_e32 v117, v133
	v_permlane32_swap_b32_e32 v119, v134
	v_permlane32_swap_b32_e32 v118, v136
	v_permlane32_swap_b32_e32 v121, v137
	s_branch .Lsqb_fon
.Lsqb_fo1:
	v_permlane32_swap_b32_e32 v46, v53
	v_permlane32_swap_b32_e32 v48, v56
	v_permlane32_swap_b32_e32 v47, v55
	v_permlane32_swap_b32_e32 v49, v57
	v_permlane32_swap_b32_e32 v42, v58
	v_permlane32_swap_b32_e32 v50, v60
	v_permlane32_swap_b32_e32 v43, v59
	v_permlane32_swap_b32_e32 v44, v61
	v_permlane32_swap_b32_e32 v38, v62
	v_permlane32_swap_b32_e32 v45, v64
	v_permlane32_swap_b32_e32 v39, v63
	v_permlane32_swap_b32_e32 v40, v65
	v_permlane32_swap_b32_e32 v41, v72
	v_permlane32_swap_b32_e32 v52, v73
	v_permlane32_swap_b32_e32 v51, v74
	v_permlane32_swap_b32_e32 v54, v75
.Lsqb_fon:
	s_nop 1
	v_max_u32_dpp v142, v177, v177 row_shr:1 row_mask:0xf bank_mask:0xf bound_ctrl:1
	s_nop 1
	v_max_u32_dpp v142, v142, v142 row_shr:2 row_mask:0xf bank_mask:0xf bound_ctrl:1
	s_nop 1
	v_max_u32_dpp v142, v142, v142 row_shr:4 row_mask:0xf bank_mask:0xf bound_ctrl:1
	s_nop 1
	v_max_u32_dpp v142, v142, v142 row_shr:8 row_mask:0xf bank_mask:0xf bound_ctrl:1
	s_nop 1
	v_max_u32_dpp v142, v142, v142 row_bcast:15 row_mask:0xa bank_mask:0xf
	s_nop 1
	v_max_u32_dpp v142, v142, v142 row_bcast:31 row_mask:0xc bank_mask:0xf
	s_nop 0
	v_readlane_b32 s19, v142, 63
	s_mov_b32 s21, 0
	s_mov_b32 s14, 0x80000001
; __device__ __forceinline__ int count_ge(const unsigned (&u)[64], unsigned cand, int nblk) {
;     int c0 = 0, c1 = 0;
;     const unsigned ts = __builtin_amdgcn_readfirstlane(cand);
; #pragma unroll
;     for (int B = 0; B < 2; ++B) {
;         if (B < nblk) {
; #pragma unroll
;             for (int i = 0; i < 32; i += 4) CNT4(c0, c1, ts, u[B * 32 + i], u[B * 32 + i + 1], u[B * 32 + i + 2], u[B * 32 + i + 3]);
;         }
;     }
;     return wave_isum(c0 + c1);
; }
.Lsqb_count:
	v_mov_b32_e32 v138, 0
	v_mov_b32_e32 v140, 0
	v_cmp_le_u32_e64 s[4:5], s14, v98
	v_cmp_le_u32_e64 s[6:7], s14, v107
	v_cmp_le_u32_e64 s[10:11], s14, v99
	v_cmp_le_u32_e64 s[26:27], s14, v108
	v_addc_co_u32_e64 v138, s[28:29], 0, v138, s[4:5]
	v_addc_co_u32_e64 v140, s[30:31], 0, v140, s[6:7]
	v_addc_co_u32_e64 v138, s[28:29], 0, v138, s[10:11]
	v_addc_co_u32_e64 v140, s[30:31], 0, v140, s[26:27]
	v_cmp_le_u32_e64 s[4:5], s14, v109
	v_cmp_le_u32_e64 s[6:7], s14, v113
	v_cmp_le_u32_e64 s[10:11], s14, v110
	v_cmp_le_u32_e64 s[26:27], s14, v114
	v_addc_co_u32_e64 v138, s[28:29], 0, v138, s[4:5]
	v_addc_co_u32_e64 v140, s[30:31], 0, v140, s[6:7]
	v_addc_co_u32_e64 v138, s[28:29], 0, v138, s[10:11]
	v_addc_co_u32_e64 v140, s[30:31], 0, v140, s[26:27]
	v_cmp_le_u32_e64 s[4:5], s14, v111
	v_cmp_le_u32_e64 s[6:7], s14, v115
	v_cmp_le_u32_e64 s[10:11], s14, v112
	v_cmp_le_u32_e64 s[26:27], s14, v116
	v_addc_co_u32_e64 v138, s[28:29], 0, v138, s[4:5]
	v_addc_co_u32_e64 v140, s[30:31], 0, v140, s[6:7]
	v_addc_co_u32_e64 v138, s[28:29], 0, v138, s[10:11]
	v_addc_co_u32_e64 v140, s[30:31], 0, v140, s[26:27]
	v_cmp_le_u32_e64 s[4:5], s14, v117
	v_cmp_le_u32_e64 s[6:7], s14, v119
	v_cmp_le_u32_e64 s[10:11], s14, v118
	v_cmp_le_u32_e64 s[26:27], s14, v121
	v_addc_co_u32_e64 v138, s[28:29], 0, v138, s[4:5]
	v_addc_co_u32_e64 v140, s[30:31], 0, v140, s[6:7]
	v_addc_co_u32_e64 v138, s[28:29], 0, v138, s[10:11]
	v_addc_co_u32_e64 v140, s[30:31], 0, v140, s[26:27]
	s_cmp_eq_u32 s32, 1
	s_cbranch_scc1 .Lsqb_red
	v_cmp_le_u32_e64 s[4:5], s14, v120
	v_cmp_le_u32_e64 s[6:7], s14, v123
	v_cmp_le_u32_e64 s[10:11], s14, v122
	v_cmp_le_u32_e64 s[26:27], s14, v124
	v_addc_co_u32_e64 v138, s[28:29], 0, v138, s[4:5]
	v_addc_co_u32_e64 v140, s[30:31], 0, v140, s[6:7]
	v_addc_co_u32_e64 v138, s[28:29], 0, v138, s[10:11]
	v_addc_co_u32_e64 v140, s[30:31], 0, v140, s[26:27]
	v_cmp_le_u32_e64 s[4:5], s14, v125
	v_cmp_le_u32_e64 s[6:7], s14, v127
	v_cmp_le_u32_e64 s[10:11], s14, v126
	v_cmp_le_u32_e64 s[26:27], s14, v128
	v_addc_co_u32_e64 v138, s[28:29], 0, v138, s[4:5]
	v_addc_co_u32_e64 v140, s[30:31], 0, v140, s[6:7]
	v_addc_co_u32_e64 v138, s[28:29], 0, v138, s[10:11]
	v_addc_co_u32_e64 v140, s[30:31], 0, v140, s[26:27]
	v_cmp_le_u32_e64 s[4:5], s14, v129
	v_cmp_le_u32_e64 s[6:7], s14, v131
	v_cmp_le_u32_e64 s[10:11], s14, v130
	v_cmp_le_u32_e64 s[26:27], s14, v132
	v_addc_co_u32_e64 v138, s[28:29], 0, v138, s[4:5]
	v_addc_co_u32_e64 v140, s[30:31], 0, v140, s[6:7]
	v_addc_co_u32_e64 v138, s[28:29], 0, v138, s[10:11]
	v_addc_co_u32_e64 v140, s[30:31], 0, v140, s[26:27]
	v_cmp_le_u32_e64 s[4:5], s14, v133
	v_cmp_le_u32_e64 s[6:7], s14, v134
	v_cmp_le_u32_e64 s[10:11], s14, v136
	v_cmp_le_u32_e64 s[26:27], s14, v137
	v_addc_co_u32_e64 v138, s[28:29], 0, v138, s[4:5]
	v_addc_co_u32_e64 v140, s[30:31], 0, v140, s[6:7]
	v_addc_co_u32_e64 v138, s[28:29], 0, v138, s[10:11]
	v_addc_co_u32_e64 v140, s[30:31], 0, v140, s[26:27]
	s_cmp_eq_u32 s32, 2
	s_cbranch_scc1 .Lsqb_red
	v_cmp_le_u32_e64 s[4:5], s14, v46
	v_cmp_le_u32_e64 s[6:7], s14, v48
	v_cmp_le_u32_e64 s[10:11], s14, v47
	v_cmp_le_u32_e64 s[26:27], s14, v49
	v_addc_co_u32_e64 v138, s[28:29], 0, v138, s[4:5]
	v_addc_co_u32_e64 v140, s[30:31], 0, v140, s[6:7]
	v_addc_co_u32_e64 v138, s[28:29], 0, v138, s[10:11]
	v_addc_co_u32_e64 v140, s[30:31], 0, v140, s[26:27]
	v_cmp_le_u32_e64 s[4:5], s14, v42
	v_cmp_le_u32_e64 s[6:7], s14, v50
	v_cmp_le_u32_e64 s[10:11], s14, v43
	v_cmp_le_u32_e64 s[26:27], s14, v44
	v_addc_co_u32_e64 v138, s[28:29], 0, v138, s[4:5]
	v_addc_co_u32_e64 v140, s[30:31], 0, v140, s[6:7]
	v_addc_co_u32_e64 v138, s[28:29], 0, v138, s[10:11]
	v_addc_co_u32_e64 v140, s[30:31], 0, v140, s[26:27]
	v_cmp_le_u32_e64 s[4:5], s14, v38
	v_cmp_le_u32_e64 s[6:7], s14, v45
	v_cmp_le_u32_e64 s[10:11], s14, v39
	v_cmp_le_u32_e64 s[26:27], s14, v40
	v_addc_co_u32_e64 v138, s[28:29], 0, v138, s[4:5]
	v_addc_co_u32_e64 v140, s[30:31], 0, v140, s[6:7]
	v_addc_co_u32_e64 v138, s[28:29], 0, v138, s[10:11]
	v_addc_co_u32_e64 v140, s[30:31], 0, v140, s[26:27]
	v_cmp_le_u32_e64 s[4:5], s14, v41
	v_cmp_le_u32_e64 s[6:7], s14, v52
	v_cmp_le_u32_e64 s[10:11], s14, v51
	v_cmp_le_u32_e64 s[26:27], s14, v54
	v_addc_co_u32_e64 v138, s[28:29], 0, v138, s[4:5]
	v_addc_co_u32_e64 v140, s[30:31], 0, v140, s[6:7]
	v_addc_co_u32_e64 v138, s[28:29], 0, v138, s[10:11]
	v_addc_co_u32_e64 v140, s[30:31], 0, v140, s[26:27]
	s_cmp_eq_u32 s32, 3
	s_cbranch_scc1 .Lsqb_red
	v_cmp_le_u32_e64 s[4:5], s14, v53
	v_cmp_le_u32_e64 s[6:7], s14, v56
	v_cmp_le_u32_e64 s[10:11], s14, v55
	v_cmp_le_u32_e64 s[26:27], s14, v57
	v_addc_co_u32_e64 v138, s[28:29], 0, v138, s[4:5]
	v_addc_co_u32_e64 v140, s[30:31], 0, v140, s[6:7]
	v_addc_co_u32_e64 v138, s[28:29], 0, v138, s[10:11]
	v_addc_co_u32_e64 v140, s[30:31], 0, v140, s[26:27]
	v_cmp_le_u32_e64 s[4:5], s14, v58
	v_cmp_le_u32_e64 s[6:7], s14, v60
	v_cmp_le_u32_e64 s[10:11], s14, v59
	v_cmp_le_u32_e64 s[26:27], s14, v61
	v_addc_co_u32_e64 v138, s[28:29], 0, v138, s[4:5]
	v_addc_co_u32_e64 v140, s[30:31], 0, v140, s[6:7]
	v_addc_co_u32_e64 v138, s[28:29], 0, v138, s[10:11]
	v_addc_co_u32_e64 v140, s[30:31], 0, v140, s[26:27]
	v_cmp_le_u32_e64 s[4:5], s14, v62
	v_cmp_le_u32_e64 s[6:7], s14, v64
	v_cmp_le_u32_e64 s[10:11], s14, v63
	v_cmp_le_u32_e64 s[26:27], s14, v65
	v_addc_co_u32_e64 v138, s[28:29], 0, v138, s[4:5]
	v_addc_co_u32_e64 v140, s[30:31], 0, v140, s[6:7]
	v_addc_co_u32_e64 v138, s[28:29], 0, v138, s[10:11]
	v_addc_co_u32_e64 v140, s[30:31], 0, v140, s[26:27]
	v_cmp_le_u32_e64 s[4:5], s14, v72
	v_cmp_le_u32_e64 s[6:7], s14, v73
	v_cmp_le_u32_e64 s[10:11], s14, v74
	v_cmp_le_u32_e64 s[26:27], s14, v75
	v_addc_co_u32_e64 v138, s[28:29], 0, v138, s[4:5]
	v_addc_co_u32_e64 v140, s[30:31], 0, v140, s[6:7]
	v_addc_co_u32_e64 v138, s[28:29], 0, v138, s[10:11]
	v_addc_co_u32_e64 v140, s[30:31], 0, v140, s[26:27]

; __device__ __forceinline__ void select_query(const unsigned (&u)[64], unsigned vmax, int q, int b, int lane, unsigned* MASKb) {
;     ...
;         if (exact) TG = T - 1u; else { TG = T; rrem = 256 - count_ge(u, T + 1u, nblk); }
;     }
;     int tbase = 0;
; #pragma unroll
;     for (int B = 0; B < 2; ++B) {
;         if (B < nblk) {
;             unsigned w = 0u; const unsigned tgs = __builtin_amdgcn_readfirstlane(TG);
; #pragma unroll
;             for (int e = 31; e >= 3; e -= 4) BIT4(w, tgs, u[B * 32 + e], u[B * 32 + e - 1], u[B * 32 + e - 2], u[B * 32 + e - 3]);
.Lsqb_fin:
	s_bitcmp1_b32 s32, 0
	s_cbranch_scc0 .Lsqb_unn
	s_cmp_lt_u32 s32, 2
	s_cbranch_scc0 .Lsqb_un1
	v_permlane32_swap_b32_e32 v98, v120
	v_permlane32_swap_b32_e32 v107, v123
	v_permlane32_swap_b32_e32 v99, v122
	v_permlane32_swap_b32_e32 v108, v124
	v_permlane32_swap_b32_e32 v109, v125
	v_permlane32_swap_b32_e32 v113, v127
	v_permlane32_swap_b32_e32 v110, v126
	v_permlane32_swap_b32_e32 v114, v128
	v_permlane32_swap_b32_e32 v111, v129
	v_permlane32_swap_b32_e32 v115, v131
	v_permlane32_swap_b32_e32 v112, v130
	v_permlane32_swap_b32_e32 v116, v132
	v_permlane32_swap_b32_e32 v117, v133
	v_permlane32_swap_b32_e32 v119, v134
	v_permlane32_swap_b32_e32 v118, v136
	v_permlane32_swap_b32_e32 v121, v137
	s_branch .Lsqb_unn
